# attention full-tile loop: staging made unconditional and the closing wait fixed at vmcnt(6) (branch tests off the tile path, byte phase kept)
# speedup vs baseline: 1.0498x; 1.0023x over previous
.Lat2_main_2:
	v_add_u32_e32 v205, s59, v203
	ds_read_b128 v[116:119], v205 offset:0
	ds_read_b128 v[120:123], v205 offset:512
	ds_read_b128 v[124:127], v205 offset:2048
	ds_read_b128 v[128:131], v205 offset:2560
	ds_read_b128 v[132:135], v205 offset:4096
	ds_read_b128 v[136:139], v205 offset:4608
	ds_read_b128 v[140:143], v205 offset:6144
	ds_read_b128 v[144:147], v205 offset:6656
	s_nop 0
	s_add_i32 s4, s25, s16
	s_mov_b32 m0, s4
	s_lshl_b32 s5, s25, 1
	global_load_lds_dwordx4 v200, s[80:81]
	s_add_i32 s5, s5, s16
	s_add_i32 s5, s5, 0x8000
	s_mov_b32 m0, s5
	s_add_i32 s5, s5, 0x2000
	global_load_lds_dwordx4 v201, s[82:83]
	s_mov_b32 m0, s5
	s_nop 0
	global_load_lds_dwordx4 v202, s[82:83]
	s_add_u32 s80, s80, 0x10000
	s_addc_u32 s81, s81, 0
	s_add_u32 s82, s82, 0x10000
	s_addc_u32 s83, s83, 0
	s_lshl_b32 s7, s59, 1
	v_add_u32_e32 v206, s7, v204
	s_waitcnt lgkmcnt(6)
	v_mfma_f32_32x32x16_bf16 v[64:79], v[116:119], v[148:151], v[100:115]
	v_mfma_f32_32x32x16_bf16 v[80:95], v[120:123], v[148:151], v[100:115]
	s_waitcnt lgkmcnt(4)
	v_mfma_f32_32x32x16_bf16 v[64:79], v[124:127], v[152:155], v[64:79]
	v_mfma_f32_32x32x16_bf16 v[80:95], v[128:131], v[152:155], v[80:95]
	s_waitcnt lgkmcnt(2)
	v_mfma_f32_32x32x16_bf16 v[64:79], v[132:135], v[156:159], v[64:79]
	v_mfma_f32_32x32x16_bf16 v[80:95], v[136:139], v[156:159], v[80:95]
	s_waitcnt lgkmcnt(0)
	v_mfma_f32_32x32x16_bf16 v[64:79], v[140:143], v[160:163], v[64:79]
	v_mfma_f32_32x32x16_bf16 v[80:95], v[144:147], v[160:163], v[80:95]
	ds_read_b64_tr_b16 v[164:165], v206 offset:0
	ds_read_b64_tr_b16 v[166:167], v206 offset:512
	ds_read_b64_tr_b16 v[168:169], v206 offset:4096
	ds_read_b64_tr_b16 v[170:171], v206 offset:4608
	ds_read_b64_tr_b16 v[172:173], v206 offset:8192
	ds_read_b64_tr_b16 v[174:175], v206 offset:8704
	ds_read_b64_tr_b16 v[176:177], v206 offset:12288
	ds_read_b64_tr_b16 v[178:179], v206 offset:12800
	ds_read_b64_tr_b16 v[180:181], v206 offset:1024
	ds_read_b64_tr_b16 v[182:183], v206 offset:1536
	ds_read_b64_tr_b16 v[184:185], v206 offset:5120
	ds_read_b64_tr_b16 v[186:187], v206 offset:5632
	ds_read_b64_tr_b16 v[188:189], v206 offset:9216
	ds_read_b64_tr_b16 v[190:191], v206 offset:9728
	ds_read_b64_tr_b16 v[192:193], v206 offset:13312
	ds_read_b64_tr_b16 v[194:195], v206 offset:13824
	s_nop 0
	s_nop 0
	v_max3_f32 v215, v64, v65, v80
	v_max3_f32 v216, v66, v67, v81
	v_max3_f32 v215, v215, v82, v83
	v_max3_f32 v216, v216, v68, v69
	v_max3_f32 v215, v215, v70, v71
	v_max3_f32 v216, v216, v84, v85
	v_max3_f32 v215, v215, v86, v87
	v_max3_f32 v216, v216, v72, v73
	v_max3_f32 v215, v215, v74, v75
	v_max3_f32 v216, v216, v88, v89
	v_max3_f32 v215, v215, v90, v91
	v_max3_f32 v216, v216, v76, v77
	v_max3_f32 v215, v215, v78, v79
	v_max3_f32 v216, v216, v92, v93
	v_max3_f32 v215, v215, v94, v95
	v_max_f32_e32 v214, v215, v216
	v_mov_b32_e32 v215, v214
	s_nop 1
	v_permlane32_swap_b32_e32 v214, v215
	s_nop 0
	v_max_f32_e32 v214, v214, v215
	v_cmp_lt_f32_e32 vcc, s62, v214
	s_cmp_lg_u64 vcc, 0
	s_cbranch_scc1 .Lat2_resc_7
.Lat2_back_8:
	v_exp_f32_e32 v64, v64
	v_exp_f32_e32 v65, v65
	v_exp_f32_e32 v66, v66
	v_exp_f32_e32 v67, v67
	v_exp_f32_e32 v68, v68
	v_exp_f32_e32 v69, v69
	v_exp_f32_e32 v70, v70
	v_exp_f32_e32 v71, v71
	s_nop 0
	v_pk_add_f32 v[232:233], v[232:233], v[64:65]
	v_pk_add_f32 v[234:235], v[234:235], v[66:67]
	v_pk_add_f32 v[232:233], v[232:233], v[68:69]
	v_pk_add_f32 v[234:235], v[234:235], v[70:71]
	v_cvt_pk_bf16_f32 v64, v64, v65
	v_cvt_pk_bf16_f32 v65, v66, v67
	v_cvt_pk_bf16_f32 v66, v68, v69
	v_cvt_pk_bf16_f32 v67, v70, v71
	s_waitcnt lgkmcnt(0)
	s_nop 0
	v_mfma_f32_32x32x16_bf16 v[0:15], v[64:67], v[164:167], v[0:15]
	v_exp_f32_e32 v72, v72
	v_exp_f32_e32 v73, v73
	v_mfma_f32_32x32x16_bf16 v[16:31], v[64:67], v[168:171], v[16:31]
	ds_read_b64_tr_b16 v[164:165], v206 offset:2048
	ds_read_b64_tr_b16 v[166:167], v206 offset:2560
	v_exp_f32_e32 v74, v74
	v_exp_f32_e32 v75, v75
	v_pk_add_f32 v[232:233], v[232:233], v[72:73]
	v_mfma_f32_32x32x16_bf16 v[32:47], v[64:67], v[172:175], v[32:47]
	ds_read_b64_tr_b16 v[168:169], v206 offset:6144
	ds_read_b64_tr_b16 v[170:171], v206 offset:6656
	v_exp_f32_e32 v76, v76
	v_exp_f32_e32 v77, v77
	v_pk_add_f32 v[234:235], v[234:235], v[74:75]
	v_mfma_f32_32x32x16_bf16 v[48:63], v[64:67], v[176:179], v[48:63]
	ds_read_b64_tr_b16 v[172:173], v206 offset:10240
	ds_read_b64_tr_b16 v[174:175], v206 offset:10752
	v_exp_f32_e32 v78, v78
	v_exp_f32_e32 v79, v79
	v_pk_add_f32 v[232:233], v[232:233], v[76:77]
	s_nop 0
	v_pk_add_f32 v[234:235], v[234:235], v[78:79]
	v_cvt_pk_bf16_f32 v72, v72, v73
	v_cvt_pk_bf16_f32 v73, v74, v75
	v_cvt_pk_bf16_f32 v74, v76, v77
	v_cvt_pk_bf16_f32 v75, v78, v79
	s_nop 1
	v_mfma_f32_32x32x16_bf16 v[0:15], v[72:75], v[180:183], v[0:15]
	ds_read_b64_tr_b16 v[176:177], v206 offset:14336
	ds_read_b64_tr_b16 v[178:179], v206 offset:14848
	v_exp_f32_e32 v80, v80
	v_exp_f32_e32 v81, v81
	v_mfma_f32_32x32x16_bf16 v[16:31], v[72:75], v[184:187], v[16:31]
	ds_read_b64_tr_b16 v[180:181], v206 offset:3072
	ds_read_b64_tr_b16 v[182:183], v206 offset:3584
	v_exp_f32_e32 v82, v82
	v_exp_f32_e32 v83, v83
	v_pk_add_f32 v[232:233], v[232:233], v[80:81]
	v_mfma_f32_32x32x16_bf16 v[32:47], v[72:75], v[188:191], v[32:47]
	ds_read_b64_tr_b16 v[184:185], v206 offset:7168
	ds_read_b64_tr_b16 v[186:187], v206 offset:7680
	v_exp_f32_e32 v84, v84
	v_exp_f32_e32 v85, v85
	v_pk_add_f32 v[234:235], v[234:235], v[82:83]
	v_mfma_f32_32x32x16_bf16 v[48:63], v[72:75], v[192:195], v[48:63]
	ds_read_b64_tr_b16 v[188:189], v206 offset:11264
	ds_read_b64_tr_b16 v[190:191], v206 offset:11776
	v_exp_f32_e32 v86, v86
	v_exp_f32_e32 v87, v87
	v_pk_add_f32 v[232:233], v[232:233], v[84:85]
	s_nop 0
	v_pk_add_f32 v[234:235], v[234:235], v[86:87]
	v_cvt_pk_bf16_f32 v80, v80, v81
	v_cvt_pk_bf16_f32 v81, v82, v83
	v_cvt_pk_bf16_f32 v82, v84, v85
	v_cvt_pk_bf16_f32 v83, v86, v87
	s_nop 1
	s_waitcnt lgkmcnt(12)
	v_mfma_f32_32x32x16_bf16 v[0:15], v[80:83], v[164:167], v[0:15]
	ds_read_b64_tr_b16 v[192:193], v206 offset:15360
	ds_read_b64_tr_b16 v[194:195], v206 offset:15872
	v_exp_f32_e32 v88, v88
	v_exp_f32_e32 v89, v89
	s_waitcnt lgkmcnt(12)
	v_mfma_f32_32x32x16_bf16 v[16:31], v[80:83], v[168:171], v[16:31]
	v_exp_f32_e32 v90, v90
	v_exp_f32_e32 v91, v91
	v_pk_add_f32 v[232:233], v[232:233], v[88:89]
	s_waitcnt lgkmcnt(10)
	v_mfma_f32_32x32x16_bf16 v[32:47], v[80:83], v[172:175], v[32:47]
	v_exp_f32_e32 v92, v92
	v_exp_f32_e32 v93, v93
	v_pk_add_f32 v[234:235], v[234:235], v[90:91]
	s_waitcnt lgkmcnt(8)
	v_mfma_f32_32x32x16_bf16 v[48:63], v[80:83], v[176:179], v[48:63]
	v_exp_f32_e32 v94, v94
	v_exp_f32_e32 v95, v95
	v_pk_add_f32 v[232:233], v[232:233], v[92:93]
	s_nop 0
	v_pk_add_f32 v[234:235], v[234:235], v[94:95]
	v_cvt_pk_bf16_f32 v88, v88, v89
	v_cvt_pk_bf16_f32 v89, v90, v91
	v_cvt_pk_bf16_f32 v90, v92, v93
	v_cvt_pk_bf16_f32 v91, v94, v95
	s_nop 1
	s_waitcnt lgkmcnt(6)
	v_mfma_f32_32x32x16_bf16 v[0:15], v[88:91], v[180:183], v[0:15]
	s_waitcnt lgkmcnt(4)
	v_mfma_f32_32x32x16_bf16 v[16:31], v[88:91], v[184:187], v[16:31]
	s_waitcnt lgkmcnt(2)
	v_mfma_f32_32x32x16_bf16 v[32:47], v[88:91], v[188:191], v[32:47]
	s_waitcnt lgkmcnt(0)
	v_mfma_f32_32x32x16_bf16 v[48:63], v[88:91], v[192:195], v[48:63]
	s_mov_b32 s4, s59
	s_mov_b32 s59, s60
	s_mov_b32 s60, s61
	s_mov_b32 s61, s25
	s_mov_b32 s25, s4
	s_add_i32 s45, s45, 1
	s_mov_b32 s62, 0x41000000
	s_mov_b32 s47, 0
	s_nop 0
	s_waitcnt vmcnt(6)
